# diff: k-step-1 V fragment reads fill the MFMA-to-VALU wait slot in the max tree instead of an s_nop
# baseline (speedup 1.0000x reference)
; #define MFMA32(a, b, c) __builtin_amdgcn_mfma_f32_32x32x16_bf16((a), (b), (c), 0, 0, 0)
; #define VFRAG(ptr, off0, STR) ({ const s16x4 lo_ = vtr((ptr) + (off0)); const s16x4 hi_ = vtr((ptr) + (off0) + 8 * (STR)); (bf16x8){lo_[0], lo_[1], lo_[2], lo_[3], hi_[0], hi_[1], hi_[2], hi_[3]}; })
; __device__ __forceinline__ void diff_unit(const Frame& F, int b, int h, int qi, float lam, int dry) {
;     ...
;             float mx = fmaxf(s0[0], s1[0]);
; #pragma unroll
;             for (int r = 1; r < 16; ++r) mx = fmaxf(mx, fmaxf(s0[r], s1[r]));
;             mx = fmaxf(mx, __shfl_xor(mx, 32));
;             const float mxs = mx * LOG2E;
;             if (__any(mxs > ms + 8.0f)) {
;                 const float msn = fmaxf(ms, mxs); const float f = __builtin_amdgcn_exp2f(ms - msn); lsum *= f; ms = msn;
; #pragma unroll
;                 for (int dt = 0; dt < 4; ++dt)
; #pragma unroll
;                     for (int r = 0; r < 16; ++r) O[dt][r] *= f;
;             }
;     ...
;                   for (int dt = 2; dt < 4; ++dt) { const bf16x8 vf = VFRAG(vb, 16 * DV_STR + 64 * dt, DV_STR); O[dt] = MFMA32(vf, pf, O[dt]); } }
.LBB0_303:
	v_max3_f32 v223, v80, v81, v82
	v_max3_f32 v223, v223, v83, v84
	v_max3_f32 v223, v223, v85, v86
	v_max3_f32 v223, v223, v87, v88
	v_max3_f32 v223, v223, v89, v90
	v_max3_f32 v223, v223, v91, v92
	v_max3_f32 v223, v223, v93, v94
	ds_read_b64_tr_b16 v[224:225], v222 offset:40064
	ds_read_b64_tr_b16 v[226:227], v222 offset:42624
	ds_read_b64_tr_b16 v[228:229], v222 offset:40128
	ds_read_b64_tr_b16 v[230:231], v222 offset:42688
	v_max3_f32 v236, v64, v65, v66
	v_max3_f32 v236, v236, v67, v68
	v_max3_f32 v236, v236, v69, v70
	v_max3_f32 v236, v236, v71, v72
	v_max3_f32 v236, v236, v73, v74
	v_max3_f32 v236, v236, v75, v76
	v_max3_f32 v236, v236, v77, v78
	v_max3_f32 v223, v223, v236, v95
	v_max_f32_e32 v223, v223, v79
	v_cmp_lt_f32_e32 vcc, 0x41000000, v223
	s_cbranch_vccz .LBB0_305
	v_mov_b32_e32 v236, v223
	s_nop 1
	v_permlane32_swap_b32_e32 v223, v236
	v_max_f32_e32 v223, v223, v236
	v_max_f32_e32 v223, 0, v223
	v_exp_f32_e64 v236, -v223
	v_add_f32_e32 v185, v185, v223
	v_pk_mul_f32 v[62:63], v[62:63], v[236:237] op_sel_hi:[1,0]
	v_pk_mul_f32 v[60:61], v[60:61], v[236:237] op_sel_hi:[1,0]
	v_pk_mul_f32 v[58:59], v[58:59], v[236:237] op_sel_hi:[1,0]
	v_pk_mul_f32 v[56:57], v[56:57], v[236:237] op_sel_hi:[1,0]
	v_pk_mul_f32 v[54:55], v[54:55], v[236:237] op_sel_hi:[1,0]
	v_pk_mul_f32 v[52:53], v[52:53], v[236:237] op_sel_hi:[1,0]
	v_pk_mul_f32 v[50:51], v[50:51], v[236:237] op_sel_hi:[1,0]
	v_pk_mul_f32 v[48:49], v[48:49], v[236:237] op_sel_hi:[1,0]
	v_pk_mul_f32 v[46:47], v[46:47], v[236:237] op_sel_hi:[1,0]
	v_pk_mul_f32 v[44:45], v[44:45], v[236:237] op_sel_hi:[1,0]
	v_pk_mul_f32 v[42:43], v[42:43], v[236:237] op_sel_hi:[1,0]
	v_pk_mul_f32 v[40:41], v[40:41], v[236:237] op_sel_hi:[1,0]
	v_pk_mul_f32 v[38:39], v[38:39], v[236:237] op_sel_hi:[1,0]
	v_pk_mul_f32 v[36:37], v[36:37], v[236:237] op_sel_hi:[1,0]
	v_pk_mul_f32 v[34:35], v[34:35], v[236:237] op_sel_hi:[1,0]
	v_pk_mul_f32 v[32:33], v[32:33], v[236:237] op_sel_hi:[1,0]
	v_pk_mul_f32 v[30:31], v[30:31], v[236:237] op_sel_hi:[1,0]
	v_pk_mul_f32 v[28:29], v[28:29], v[236:237] op_sel_hi:[1,0]
	v_pk_mul_f32 v[26:27], v[26:27], v[236:237] op_sel_hi:[1,0]
	v_pk_mul_f32 v[24:25], v[24:25], v[236:237] op_sel_hi:[1,0]
	v_pk_mul_f32 v[22:23], v[22:23], v[236:237] op_sel_hi:[1,0]
	v_pk_mul_f32 v[20:21], v[20:21], v[236:237] op_sel_hi:[1,0]
	v_pk_mul_f32 v[18:19], v[18:19], v[236:237] op_sel_hi:[1,0]
	v_pk_mul_f32 v[16:17], v[16:17], v[236:237] op_sel_hi:[1,0]
	v_pk_mul_f32 v[14:15], v[14:15], v[236:237] op_sel_hi:[1,0]
	v_pk_mul_f32 v[12:13], v[12:13], v[236:237] op_sel_hi:[1,0]
	v_pk_mul_f32 v[10:11], v[10:11], v[236:237] op_sel_hi:[1,0]
	v_pk_mul_f32 v[8:9], v[8:9], v[236:237] op_sel_hi:[1,0]
	v_pk_mul_f32 v[6:7], v[6:7], v[236:237] op_sel_hi:[1,0]
	v_pk_mul_f32 v[4:5], v[4:5], v[236:237] op_sel_hi:[1,0]
	v_pk_mul_f32 v[2:3], v[2:3], v[236:237] op_sel_hi:[1,0]
	v_pk_mul_f32 v[0:1], v[0:1], v[236:237] op_sel_hi:[1,0]
	v_mul_f32_e32 v158, v158, v236
	v_sub_f32_e32 v64, v64, v223
	v_sub_f32_e32 v65, v65, v223
	v_sub_f32_e32 v66, v66, v223
	v_sub_f32_e32 v67, v67, v223
	v_sub_f32_e32 v68, v68, v223
	v_sub_f32_e32 v69, v69, v223
	v_sub_f32_e32 v70, v70, v223
	v_sub_f32_e32 v71, v71, v223
	v_sub_f32_e32 v72, v72, v223
	v_sub_f32_e32 v73, v73, v223
	v_sub_f32_e32 v74, v74, v223
	v_sub_f32_e32 v75, v75, v223
	v_sub_f32_e32 v76, v76, v223
	v_sub_f32_e32 v77, v77, v223
	v_sub_f32_e32 v78, v78, v223
	v_sub_f32_e32 v79, v79, v223
	v_sub_f32_e32 v80, v80, v223
	v_sub_f32_e32 v81, v81, v223
	v_sub_f32_e32 v82, v82, v223
	v_sub_f32_e32 v83, v83, v223
	v_sub_f32_e32 v84, v84, v223
	v_sub_f32_e32 v85, v85, v223
	v_sub_f32_e32 v86, v86, v223
	v_sub_f32_e32 v87, v87, v223
	v_sub_f32_e32 v88, v88, v223
	v_sub_f32_e32 v89, v89, v223
	v_sub_f32_e32 v90, v90, v223
	v_sub_f32_e32 v91, v91, v223
	v_sub_f32_e32 v92, v92, v223
	v_sub_f32_e32 v93, v93, v223
	v_sub_f32_e32 v94, v94, v223
	v_sub_f32_e32 v95, v95, v223
	v_sub_f32_e32 v238, v238, v223
	v_sub_f32_e32 v239, v239, v223
	v_sub_f32_e32 v240, v240, v223
	v_sub_f32_e32 v241, v241, v223
	v_sub_f32_e32 v242, v242, v223
	v_sub_f32_e32 v243, v243, v223
	v_sub_f32_e32 v244, v244, v223
	v_sub_f32_e32 v245, v245, v223
	v_sub_f32_e32 v246, v246, v223
	v_sub_f32_e32 v247, v247, v223
	v_sub_f32_e32 v248, v248, v223
	v_sub_f32_e32 v249, v249, v223
	v_sub_f32_e32 v250, v250, v223
	v_sub_f32_e32 v251, v251, v223
	v_sub_f32_e32 v252, v252, v223
	v_sub_f32_e32 v253, v253, v223
; #define MFMA32(a, b, c) __builtin_amdgcn_mfma_f32_32x32x16_bf16((a), (b), (c), 0, 0, 0)
; #define VFRAG(ptr, off0, STR) ({ const s16x4 lo_ = vtr((ptr) + (off0)); const s16x4 hi_ = vtr((ptr) + (off0) + 8 * (STR)); (bf16x8){lo_[0], lo_[1], lo_[2], lo_[3], hi_[0], hi_[1], hi_[2], hi_[3]}; })
; __device__ __forceinline__ void diff_unit(const Frame& F, int b, int h, int qi, float lam, int dry) {
;     ...
;             float ps = 0.f;
; #pragma unroll
;             for (int r = 0; r < 16; ++r) { s0[r] = __builtin_amdgcn_exp2f(s0[r] * LOG2E - ms); ps += s0[r]; }
;             if (!meta) {
; #pragma unroll
;                 for (int r = 0; r < 16; ++r) { s1[r] = __builtin_amdgcn_exp2f(s1[r] * LOG2E - ms); ps += s1[r]; }
;             }
;             lsum += ps;
;             __builtin_amdgcn_s_setprio(1);
;             { const bf16x8 pf = pack_step(s0, 0);
;               O[0] = MFMA32(vpre0, pf, O[0]); O[1] = MFMA32(vpre1, pf, O[1]); O[2] = MFMA32(vpre2, pf, O[2]); O[3] = MFMA32(vpre3, pf, O[3]); }
;             if (!meta) {
;                 { const bf16x8 pf = pack_step(s0, 1);
;                   O[0] = MFMA32(vprf0, pf, O[0]); O[1] = MFMA32(vprf1, pf, O[1]);
; #pragma unroll
;                   for (int dt = 2; dt < 4; ++dt) { const bf16x8 vf = VFRAG(vb, 16 * DV_STR + 64 * dt, DV_STR); O[dt] = MFMA32(vf, pf, O[dt]); } }
; #pragma unroll
;                 for (int s2 = 0; s2 < 2; ++s2) { const bf16x8 pf = pack_step(s1, s2);
; #pragma unroll
;                     for (int dt = 0; dt < 4; ++dt) { const bf16x8 vf = VFRAG(vb, (32 + 16 * s2) * DV_STR + 64 * dt, DV_STR); O[dt] = MFMA32(vf, pf, O[dt]); } }
;             }
;             __builtin_amdgcn_s_setprio(0);
.LBB0_305:
	v_exp_f32_e32 v80, v80
	v_exp_f32_e32 v81, v81
	v_exp_f32_e32 v82, v82
	v_exp_f32_e32 v83, v83
	v_exp_f32_e32 v84, v84
	v_exp_f32_e32 v85, v85
	v_exp_f32_e32 v86, v86
	v_exp_f32_e32 v87, v87
	v_add_f32_e32 v236, v80, v82
	v_add_f32_e32 v237, v81, v83
	s_setprio 1
	v_cvt_pk_bf16_f32 v232, v80, v81
	v_cvt_pk_bf16_f32 v233, v82, v83
	v_cvt_pk_bf16_f32 v234, v84, v85
	v_cvt_pk_bf16_f32 v235, v86, v87
	v_add_f32_e32 v236, v236, v84
	v_add_f32_e32 v237, v237, v85
	v_add_f32_e32 v236, v236, v86
	v_add_f32_e32 v237, v237, v87
	v_mfma_f32_32x32x16_bf16 v[48:63], v[148:151], v[232:235], v[48:63]
	ds_read_b64_tr_b16 v[148:149], v222 offset:45056
	ds_read_b64_tr_b16 v[150:151], v222 offset:47616
	v_exp_f32_e32 v88, v88
	v_exp_f32_e32 v89, v89
	v_mfma_f32_32x32x16_bf16 v[32:47], v[144:147], v[232:235], v[32:47]
	ds_read_b64_tr_b16 v[144:145], v222 offset:45120
	ds_read_b64_tr_b16 v[146:147], v222 offset:47680
	v_exp_f32_e32 v90, v90
	v_exp_f32_e32 v91, v91
	v_add_f32_e32 v236, v236, v88
	v_add_f32_e32 v237, v237, v89
	v_cvt_pk_bf16_f32 v80, v88, v89
	v_mfma_f32_32x32x16_bf16 v[16:31], v[140:143], v[232:235], v[16:31]
	ds_read_b64_tr_b16 v[140:141], v222 offset:45184
	ds_read_b64_tr_b16 v[142:143], v222 offset:47744
	v_exp_f32_e32 v92, v92
	v_exp_f32_e32 v93, v93
	v_add_f32_e32 v236, v236, v90
	v_add_f32_e32 v237, v237, v91
	v_cvt_pk_bf16_f32 v81, v90, v91
	v_mfma_f32_32x32x16_bf16 v[0:15], v[136:139], v[232:235], v[0:15]
	ds_read_b64_tr_b16 v[136:137], v222 offset:45248
	ds_read_b64_tr_b16 v[138:139], v222 offset:47808
	v_exp_f32_e32 v94, v94
	v_exp_f32_e32 v95, v95
	v_add_f32_e32 v236, v236, v92
	v_add_f32_e32 v237, v237, v93
	v_cvt_pk_bf16_f32 v82, v92, v93
	v_cvt_pk_bf16_f32 v83, v94, v95
	v_add_f32_e32 v236, v236, v94
	v_add_f32_e32 v237, v237, v95
	s_nop 0
	v_mfma_f32_32x32x16_bf16 v[48:63], v[128:131], v[80:83], v[48:63]
	ds_read_b64_tr_b16 v[128:129], v222 offset:50176
	ds_read_b64_tr_b16 v[130:131], v222 offset:52736
	v_exp_f32_e32 v64, v64
	v_exp_f32_e32 v65, v65
	v_mfma_f32_32x32x16_bf16 v[32:47], v[132:135], v[80:83], v[32:47]
	ds_read_b64_tr_b16 v[132:133], v222 offset:50240
	ds_read_b64_tr_b16 v[134:135], v222 offset:52800
	v_exp_f32_e32 v66, v66
	v_exp_f32_e32 v67, v67
	v_add_f32_e32 v236, v236, v64
	v_add_f32_e32 v237, v237, v65
	v_cvt_pk_bf16_f32 v84, v64, v65
	s_waitcnt lgkmcnt(14)
	v_mfma_f32_32x32x16_bf16 v[16:31], v[224:227], v[80:83], v[16:31]
	ds_read_b64_tr_b16 v[224:225], v222 offset:50304
	ds_read_b64_tr_b16 v[226:227], v222 offset:52864
	v_exp_f32_e32 v68, v68
	v_exp_f32_e32 v69, v69
	v_add_f32_e32 v236, v236, v66
	v_add_f32_e32 v237, v237, v67
	v_cvt_pk_bf16_f32 v85, v66, v67
	s_waitcnt lgkmcnt(14)
	v_mfma_f32_32x32x16_bf16 v[0:15], v[228:231], v[80:83], v[0:15]
	ds_read_b64_tr_b16 v[228:229], v222 offset:50368
	ds_read_b64_tr_b16 v[230:231], v222 offset:52928
	v_exp_f32_e32 v70, v70
	v_exp_f32_e32 v71, v71
	v_add_f32_e32 v236, v236, v68
	v_add_f32_e32 v237, v237, v69
	v_cvt_pk_bf16_f32 v86, v68, v69
	v_cvt_pk_bf16_f32 v87, v70, v71
	v_add_f32_e32 v236, v236, v70
	v_add_f32_e32 v237, v237, v71
	s_nop 0
	s_waitcnt lgkmcnt(14)
	v_mfma_f32_32x32x16_bf16 v[48:63], v[148:151], v[84:87], v[48:63]
	v_exp_f32_e32 v72, v72
	v_exp_f32_e32 v73, v73
	s_waitcnt lgkmcnt(12)
	v_mfma_f32_32x32x16_bf16 v[32:47], v[144:147], v[84:87], v[32:47]
	v_exp_f32_e32 v74, v74
	v_exp_f32_e32 v75, v75
	v_add_f32_e32 v236, v236, v72
	v_add_f32_e32 v237, v237, v73
	v_cvt_pk_bf16_f32 v232, v72, v73
	s_waitcnt lgkmcnt(10)
	v_mfma_f32_32x32x16_bf16 v[16:31], v[140:143], v[84:87], v[16:31]
	v_exp_f32_e32 v76, v76
	v_exp_f32_e32 v77, v77
	v_add_f32_e32 v236, v236, v74
	v_add_f32_e32 v237, v237, v75
	v_cvt_pk_bf16_f32 v233, v74, v75
	s_waitcnt lgkmcnt(8)
	v_mfma_f32_32x32x16_bf16 v[0:15], v[136:139], v[84:87], v[0:15]
	v_exp_f32_e32 v78, v78
	v_exp_f32_e32 v79, v79
	v_add_f32_e32 v236, v236, v76
	v_add_f32_e32 v237, v237, v77
	v_cvt_pk_bf16_f32 v234, v76, v77
	v_cvt_pk_bf16_f32 v235, v78, v79
	v_add_f32_e32 v236, v236, v78
	v_add_f32_e32 v237, v237, v79
	v_add_f32_e32 v223, v236, v237
	v_add_f32_e32 v158, v158, v223
	s_waitcnt lgkmcnt(6)
	v_mfma_f32_32x32x16_bf16 v[48:63], v[128:131], v[232:235], v[48:63]
	s_waitcnt lgkmcnt(4)
	v_mfma_f32_32x32x16_bf16 v[32:47], v[132:135], v[232:235], v[32:47]
	s_waitcnt lgkmcnt(2)
	v_mfma_f32_32x32x16_bf16 v[16:31], v[224:227], v[232:235], v[16:31]
	s_waitcnt lgkmcnt(0)
	v_mfma_f32_32x32x16_bf16 v[0:15], v[228:231], v[232:235], v[0:15]
	s_setprio 0
	s_andn2_b64 vcc, exec, s[66:67]
	s_cbranch_vccnz .LBB0_296

; #define MFMA32(a, b, c) __builtin_amdgcn_mfma_f32_32x32x16_bf16((a), (b), (c), 0, 0, 0)
; #define VFRAG(ptr, off0, STR) ({ const s16x4 lo_ = vtr((ptr) + (off0)); const s16x4 hi_ = vtr((ptr) + (off0) + 8 * (STR)); (bf16x8){lo_[0], lo_[1], lo_[2], lo_[3], hi_[0], hi_[1], hi_[2], hi_[3]}; })
; __device__ __forceinline__ void diff_unit(const Frame& F, int b, int h, int qi, float lam, int dry) {
;     ...
;             float mx = fmaxf(s0[0], s1[0]);
; #pragma unroll
;             for (int r = 1; r < 16; ++r) mx = fmaxf(mx, fmaxf(s0[r], s1[r]));
;             mx = fmaxf(mx, __shfl_xor(mx, 32));
;             const float mxs = mx * LOG2E;
;             if (__any(mxs > ms + 8.0f)) {
;                 const float msn = fmaxf(ms, mxs); const float f = __builtin_amdgcn_exp2f(ms - msn); lsum *= f; ms = msn;
; #pragma unroll
;                 for (int dt = 0; dt < 4; ++dt)
; #pragma unroll
;                     for (int r = 0; r < 16; ++r) O[dt][r] *= f;
;             }
;     ...
;                   for (int dt = 2; dt < 4; ++dt) { const bf16x8 vf = VFRAG(vb, 16 * DV_STR + 64 * dt, DV_STR); O[dt] = MFMA32(vf, pf, O[dt]); } }
.LBB0_322:
	v_max3_f32 v189, v80, v81, v82
	v_max3_f32 v189, v189, v83, v84
	v_max3_f32 v189, v189, v85, v86
	v_max3_f32 v189, v189, v87, v88
	v_max3_f32 v189, v189, v89, v90
	v_max3_f32 v189, v189, v91, v92
	v_max3_f32 v189, v189, v93, v94
	ds_read_b64_tr_b16 v[190:191], v188 offset:40064
	ds_read_b64_tr_b16 v[192:193], v188 offset:42624
	ds_read_b64_tr_b16 v[194:195], v188 offset:40128
	ds_read_b64_tr_b16 v[196:197], v188 offset:42688
	v_max3_f32 v202, v64, v65, v66
	v_max3_f32 v202, v202, v67, v68
	v_max3_f32 v202, v202, v69, v70
	v_max3_f32 v202, v202, v71, v72
	v_max3_f32 v202, v202, v73, v74
	v_max3_f32 v202, v202, v75, v76
	v_max3_f32 v202, v202, v77, v78
	v_max3_f32 v189, v189, v202, v95
	v_max_f32_e32 v189, v189, v79
	v_cmp_lt_f32_e32 vcc, 0x41000000, v189
	s_cbranch_vccz .LBB0_324
	v_mov_b32_e32 v202, v189
	s_nop 1
	v_permlane32_swap_b32_e32 v189, v202
	v_max_f32_e32 v189, v189, v202
	v_max_f32_e32 v189, 0, v189
	v_exp_f32_e64 v202, -v189
	v_add_f32_e32 v158, v158, v189
	v_pk_mul_f32 v[62:63], v[62:63], v[202:203] op_sel_hi:[1,0]
	v_pk_mul_f32 v[60:61], v[60:61], v[202:203] op_sel_hi:[1,0]
	v_pk_mul_f32 v[58:59], v[58:59], v[202:203] op_sel_hi:[1,0]
	v_pk_mul_f32 v[56:57], v[56:57], v[202:203] op_sel_hi:[1,0]
	v_pk_mul_f32 v[54:55], v[54:55], v[202:203] op_sel_hi:[1,0]
	v_pk_mul_f32 v[52:53], v[52:53], v[202:203] op_sel_hi:[1,0]
	v_pk_mul_f32 v[50:51], v[50:51], v[202:203] op_sel_hi:[1,0]
	v_pk_mul_f32 v[48:49], v[48:49], v[202:203] op_sel_hi:[1,0]
	v_pk_mul_f32 v[46:47], v[46:47], v[202:203] op_sel_hi:[1,0]
	v_pk_mul_f32 v[44:45], v[44:45], v[202:203] op_sel_hi:[1,0]
	v_pk_mul_f32 v[42:43], v[42:43], v[202:203] op_sel_hi:[1,0]
	v_pk_mul_f32 v[40:41], v[40:41], v[202:203] op_sel_hi:[1,0]
	v_pk_mul_f32 v[38:39], v[38:39], v[202:203] op_sel_hi:[1,0]
	v_pk_mul_f32 v[36:37], v[36:37], v[202:203] op_sel_hi:[1,0]
	v_pk_mul_f32 v[34:35], v[34:35], v[202:203] op_sel_hi:[1,0]
	v_pk_mul_f32 v[32:33], v[32:33], v[202:203] op_sel_hi:[1,0]
	v_pk_mul_f32 v[30:31], v[30:31], v[202:203] op_sel_hi:[1,0]
	v_pk_mul_f32 v[28:29], v[28:29], v[202:203] op_sel_hi:[1,0]
	v_pk_mul_f32 v[26:27], v[26:27], v[202:203] op_sel_hi:[1,0]
	v_pk_mul_f32 v[24:25], v[24:25], v[202:203] op_sel_hi:[1,0]
	v_pk_mul_f32 v[22:23], v[22:23], v[202:203] op_sel_hi:[1,0]
	v_pk_mul_f32 v[20:21], v[20:21], v[202:203] op_sel_hi:[1,0]
	v_pk_mul_f32 v[18:19], v[18:19], v[202:203] op_sel_hi:[1,0]
	v_pk_mul_f32 v[16:17], v[16:17], v[202:203] op_sel_hi:[1,0]
	v_pk_mul_f32 v[14:15], v[14:15], v[202:203] op_sel_hi:[1,0]
	v_pk_mul_f32 v[12:13], v[12:13], v[202:203] op_sel_hi:[1,0]
	v_pk_mul_f32 v[10:11], v[10:11], v[202:203] op_sel_hi:[1,0]
	v_pk_mul_f32 v[8:9], v[8:9], v[202:203] op_sel_hi:[1,0]
	v_pk_mul_f32 v[6:7], v[6:7], v[202:203] op_sel_hi:[1,0]
	v_pk_mul_f32 v[4:5], v[4:5], v[202:203] op_sel_hi:[1,0]
	v_pk_mul_f32 v[2:3], v[2:3], v[202:203] op_sel_hi:[1,0]
	v_pk_mul_f32 v[0:1], v[0:1], v[202:203] op_sel_hi:[1,0]
	v_mul_f32_e32 v153, v153, v202
	v_sub_f32_e32 v64, v64, v189
	v_sub_f32_e32 v65, v65, v189
	v_sub_f32_e32 v66, v66, v189
	v_sub_f32_e32 v67, v67, v189
	v_sub_f32_e32 v68, v68, v189
	v_sub_f32_e32 v69, v69, v189
	v_sub_f32_e32 v70, v70, v189
	v_sub_f32_e32 v71, v71, v189
	v_sub_f32_e32 v72, v72, v189
	v_sub_f32_e32 v73, v73, v189
	v_sub_f32_e32 v74, v74, v189
	v_sub_f32_e32 v75, v75, v189
	v_sub_f32_e32 v76, v76, v189
	v_sub_f32_e32 v77, v77, v189
	v_sub_f32_e32 v78, v78, v189
	v_sub_f32_e32 v79, v79, v189
	v_sub_f32_e32 v80, v80, v189
	v_sub_f32_e32 v81, v81, v189
	v_sub_f32_e32 v82, v82, v189
	v_sub_f32_e32 v83, v83, v189
	v_sub_f32_e32 v84, v84, v189
	v_sub_f32_e32 v85, v85, v189
	v_sub_f32_e32 v86, v86, v189
	v_sub_f32_e32 v87, v87, v189
	v_sub_f32_e32 v88, v88, v189
	v_sub_f32_e32 v89, v89, v189
	v_sub_f32_e32 v90, v90, v189
	v_sub_f32_e32 v91, v91, v189
	v_sub_f32_e32 v92, v92, v189
	v_sub_f32_e32 v93, v93, v189
	v_sub_f32_e32 v94, v94, v189
	v_sub_f32_e32 v95, v95, v189
	v_sub_f32_e32 v238, v238, v189
	v_sub_f32_e32 v239, v239, v189
	v_sub_f32_e32 v240, v240, v189
	v_sub_f32_e32 v241, v241, v189
	v_sub_f32_e32 v242, v242, v189
	v_sub_f32_e32 v243, v243, v189
	v_sub_f32_e32 v244, v244, v189
	v_sub_f32_e32 v245, v245, v189
	v_sub_f32_e32 v246, v246, v189
	v_sub_f32_e32 v247, v247, v189
	v_sub_f32_e32 v248, v248, v189
	v_sub_f32_e32 v249, v249, v189
	v_sub_f32_e32 v250, v250, v189
	v_sub_f32_e32 v251, v251, v189
	v_sub_f32_e32 v252, v252, v189
	v_sub_f32_e32 v253, v253, v189
; #define MFMA32(a, b, c) __builtin_amdgcn_mfma_f32_32x32x16_bf16((a), (b), (c), 0, 0, 0)
; #define VFRAG(ptr, off0, STR) ({ const s16x4 lo_ = vtr((ptr) + (off0)); const s16x4 hi_ = vtr((ptr) + (off0) + 8 * (STR)); (bf16x8){lo_[0], lo_[1], lo_[2], lo_[3], hi_[0], hi_[1], hi_[2], hi_[3]}; })
; __device__ __forceinline__ void diff_unit(const Frame& F, int b, int h, int qi, float lam, int dry) {
;     ...
;             float ps = 0.f;
; #pragma unroll
;             for (int r = 0; r < 16; ++r) { s0[r] = __builtin_amdgcn_exp2f(s0[r] * LOG2E - ms); ps += s0[r]; }
;             if (!meta) {
; #pragma unroll
;                 for (int r = 0; r < 16; ++r) { s1[r] = __builtin_amdgcn_exp2f(s1[r] * LOG2E - ms); ps += s1[r]; }
;             }
;             lsum += ps;
;             __builtin_amdgcn_s_setprio(1);
;             { const bf16x8 pf = pack_step(s0, 0);
;               O[0] = MFMA32(vpre0, pf, O[0]); O[1] = MFMA32(vpre1, pf, O[1]); O[2] = MFMA32(vpre2, pf, O[2]); O[3] = MFMA32(vpre3, pf, O[3]); }
;             if (!meta) {
;                 { const bf16x8 pf = pack_step(s0, 1);
;                   O[0] = MFMA32(vprf0, pf, O[0]); O[1] = MFMA32(vprf1, pf, O[1]);
; #pragma unroll
;                   for (int dt = 2; dt < 4; ++dt) { const bf16x8 vf = VFRAG(vb, 16 * DV_STR + 64 * dt, DV_STR); O[dt] = MFMA32(vf, pf, O[dt]); } }
; #pragma unroll
;                 for (int s2 = 0; s2 < 2; ++s2) { const bf16x8 pf = pack_step(s1, s2);
; #pragma unroll
;                     for (int dt = 0; dt < 4; ++dt) { const bf16x8 vf = VFRAG(vb, (32 + 16 * s2) * DV_STR + 64 * dt, DV_STR); O[dt] = MFMA32(vf, pf, O[dt]); } }
;             }
;             __builtin_amdgcn_s_setprio(0);
.LBB0_324:
	v_exp_f32_e32 v80, v80
	v_exp_f32_e32 v81, v81
	v_exp_f32_e32 v82, v82
	v_exp_f32_e32 v83, v83
	v_exp_f32_e32 v84, v84
	v_exp_f32_e32 v85, v85
	v_exp_f32_e32 v86, v86
	v_exp_f32_e32 v87, v87
	v_add_f32_e32 v202, v80, v82
	v_add_f32_e32 v203, v81, v83
	s_setprio 1
	v_cvt_pk_bf16_f32 v198, v80, v81
	v_cvt_pk_bf16_f32 v199, v82, v83
	v_cvt_pk_bf16_f32 v200, v84, v85
	v_cvt_pk_bf16_f32 v201, v86, v87
	v_add_f32_e32 v202, v202, v84
	v_add_f32_e32 v203, v203, v85
	v_add_f32_e32 v202, v202, v86
	v_add_f32_e32 v203, v203, v87
	v_mfma_f32_32x32x16_bf16 v[48:63], v[148:151], v[198:201], v[48:63]
	ds_read_b64_tr_b16 v[148:149], v188 offset:45056
	ds_read_b64_tr_b16 v[150:151], v188 offset:47616
	v_exp_f32_e32 v88, v88
	v_exp_f32_e32 v89, v89
	v_mfma_f32_32x32x16_bf16 v[32:47], v[144:147], v[198:201], v[32:47]
	ds_read_b64_tr_b16 v[144:145], v188 offset:45120
	ds_read_b64_tr_b16 v[146:147], v188 offset:47680
	v_exp_f32_e32 v90, v90
	v_exp_f32_e32 v91, v91
	v_add_f32_e32 v202, v202, v88
	v_add_f32_e32 v203, v203, v89
	v_cvt_pk_bf16_f32 v80, v88, v89
	v_mfma_f32_32x32x16_bf16 v[16:31], v[140:143], v[198:201], v[16:31]
	ds_read_b64_tr_b16 v[140:141], v188 offset:45184
	ds_read_b64_tr_b16 v[142:143], v188 offset:47744
	v_exp_f32_e32 v92, v92
	v_exp_f32_e32 v93, v93
	v_add_f32_e32 v202, v202, v90
	v_add_f32_e32 v203, v203, v91
	v_cvt_pk_bf16_f32 v81, v90, v91
	v_mfma_f32_32x32x16_bf16 v[0:15], v[136:139], v[198:201], v[0:15]
	ds_read_b64_tr_b16 v[136:137], v188 offset:45248
	ds_read_b64_tr_b16 v[138:139], v188 offset:47808
	v_exp_f32_e32 v94, v94
	v_exp_f32_e32 v95, v95
	v_add_f32_e32 v202, v202, v92
	v_add_f32_e32 v203, v203, v93
	v_cvt_pk_bf16_f32 v82, v92, v93
	v_cvt_pk_bf16_f32 v83, v94, v95
	v_add_f32_e32 v202, v202, v94
	v_add_f32_e32 v203, v203, v95
	s_nop 0
	v_mfma_f32_32x32x16_bf16 v[48:63], v[128:131], v[80:83], v[48:63]
	ds_read_b64_tr_b16 v[128:129], v188 offset:50176
	ds_read_b64_tr_b16 v[130:131], v188 offset:52736
	v_exp_f32_e32 v64, v64
	v_exp_f32_e32 v65, v65
	v_mfma_f32_32x32x16_bf16 v[32:47], v[132:135], v[80:83], v[32:47]
	ds_read_b64_tr_b16 v[132:133], v188 offset:50240
	ds_read_b64_tr_b16 v[134:135], v188 offset:52800
	v_exp_f32_e32 v66, v66
	v_exp_f32_e32 v67, v67
	v_add_f32_e32 v202, v202, v64
	v_add_f32_e32 v203, v203, v65
	v_cvt_pk_bf16_f32 v84, v64, v65
	s_waitcnt lgkmcnt(14)
	v_mfma_f32_32x32x16_bf16 v[16:31], v[190:193], v[80:83], v[16:31]
	ds_read_b64_tr_b16 v[190:191], v188 offset:50304
	ds_read_b64_tr_b16 v[192:193], v188 offset:52864
	v_exp_f32_e32 v68, v68
	v_exp_f32_e32 v69, v69
	v_add_f32_e32 v202, v202, v66
	v_add_f32_e32 v203, v203, v67
	v_cvt_pk_bf16_f32 v85, v66, v67
	s_waitcnt lgkmcnt(14)
	v_mfma_f32_32x32x16_bf16 v[0:15], v[194:197], v[80:83], v[0:15]
	ds_read_b64_tr_b16 v[194:195], v188 offset:50368
	ds_read_b64_tr_b16 v[196:197], v188 offset:52928
	v_exp_f32_e32 v70, v70
	v_exp_f32_e32 v71, v71
	v_add_f32_e32 v202, v202, v68
	v_add_f32_e32 v203, v203, v69
	v_cvt_pk_bf16_f32 v86, v68, v69
	v_cvt_pk_bf16_f32 v87, v70, v71
	v_add_f32_e32 v202, v202, v70
	v_add_f32_e32 v203, v203, v71
	s_nop 0
	s_waitcnt lgkmcnt(14)
	v_mfma_f32_32x32x16_bf16 v[48:63], v[148:151], v[84:87], v[48:63]
	v_exp_f32_e32 v72, v72
	v_exp_f32_e32 v73, v73
	s_waitcnt lgkmcnt(12)
	v_mfma_f32_32x32x16_bf16 v[32:47], v[144:147], v[84:87], v[32:47]
	v_exp_f32_e32 v74, v74
	v_exp_f32_e32 v75, v75
	v_add_f32_e32 v202, v202, v72
	v_add_f32_e32 v203, v203, v73
	v_cvt_pk_bf16_f32 v198, v72, v73
	s_waitcnt lgkmcnt(10)
	v_mfma_f32_32x32x16_bf16 v[16:31], v[140:143], v[84:87], v[16:31]
	v_exp_f32_e32 v76, v76
	v_exp_f32_e32 v77, v77
	v_add_f32_e32 v202, v202, v74
	v_add_f32_e32 v203, v203, v75
	v_cvt_pk_bf16_f32 v199, v74, v75
	s_waitcnt lgkmcnt(8)
	v_mfma_f32_32x32x16_bf16 v[0:15], v[136:139], v[84:87], v[0:15]
	v_exp_f32_e32 v78, v78
	v_exp_f32_e32 v79, v79
	v_add_f32_e32 v202, v202, v76
	v_add_f32_e32 v203, v203, v77
	v_cvt_pk_bf16_f32 v200, v76, v77
	v_cvt_pk_bf16_f32 v201, v78, v79
	v_add_f32_e32 v202, v202, v78
	v_add_f32_e32 v203, v203, v79
	v_add_f32_e32 v189, v202, v203
	v_add_f32_e32 v153, v153, v189
	s_waitcnt lgkmcnt(6)
	v_mfma_f32_32x32x16_bf16 v[48:63], v[128:131], v[198:201], v[48:63]
	s_waitcnt lgkmcnt(4)
	v_mfma_f32_32x32x16_bf16 v[32:47], v[132:135], v[198:201], v[32:47]
	s_waitcnt lgkmcnt(2)
	v_mfma_f32_32x32x16_bf16 v[16:31], v[190:193], v[198:201], v[16:31]
	s_waitcnt lgkmcnt(0)
	v_mfma_f32_32x32x16_bf16 v[0:15], v[194:197], v[198:201], v[0:15]
	s_setprio 0
	s_andn2_b64 vcc, exec, s[90:91]
	s_cbranch_vccnz .LBB0_315
